# experiment: nt loads for the once-read sigmoid gates in the branch GEMM (mid-K hook and epilogue)
# speedup vs baseline: 1.0032x; 1.0032x over previous
.LBB0_902:
	s_cmpk_lg_i32 s28, 0x800
	s_cbranch_scc1 .LBB0_901
	v_mov_b32_e32 v130, 0
	s_nop 0
	v_add_u32_e32 v189, v130, v188
	v_mad_i64_i32 v[130:131], s[6:7], v189, s46, v[192:193]
	global_load_dwordx4 v[202:205], v[130:131], off nt
	v_mad_i64_i32 v[132:133], s[6:7], v189, s46, v[190:191]
	global_load_dwordx4 v[206:209], v[132:133], off nt
	global_load_dwordx4 v[210:213], v[130:131], off offset:256 nt
	global_load_dwordx4 v[214:217], v[132:133], off offset:256 nt
	v_add_u32_e32 v134, 16, v189
	v_add_u32_e32 v136, 32, v189
	v_add_u32_e32 v138, 48, v189
	v_mad_i64_i32 v[130:131], s[6:7], v134, s46, v[190:191]
	v_mad_i64_i32 v[132:133], s[6:7], v134, s46, v[192:193]
	v_mad_i64_i32 v[134:135], s[6:7], v136, s46, v[190:191]
	v_mad_i64_i32 v[136:137], s[6:7], v136, s46, v[192:193]
	v_mad_i64_i32 v[142:143], s[6:7], v138, s46, v[190:191]
	v_mad_i64_i32 v[226:227], s[6:7], v138, s46, v[192:193]
	global_load_dwordx4 v[218:221], v[130:131], off nt
	global_load_dwordx4 v[162:165], v[130:131], off offset:256 nt
	global_load_dwordx4 v[222:225], v[132:133], off nt
	global_load_dwordx4 v[166:169], v[132:133], off offset:256 nt
	global_load_dwordx4 v[154:157], v[134:135], off nt
	global_load_dwordx4 v[146:149], v[134:135], off offset:256 nt
	global_load_dwordx4 v[158:161], v[136:137], off nt
	global_load_dwordx4 v[150:153], v[136:137], off offset:256 nt
	global_load_dwordx4 v[138:141], v[142:143], off nt
	global_load_dwordx4 v[130:133], v[142:143], off offset:256 nt
	s_nop 0
	global_load_dwordx4 v[142:145], v[226:227], off nt
	global_load_dwordx4 v[134:137], v[226:227], off offset:256 nt
	s_waitcnt vmcnt(0)
	v_lshlrev_b32_e32 v201, 16, v202
	v_and_b32_e32 v228, 0xffff0000, v202
	v_lshlrev_b32_e32 v226, 16, v206
	v_and_b32_e32 v227, 0xffff0000, v206
	v_lshlrev_b32_e32 v229, 16, v203
	v_and_b32_e32 v230, 0xffff0000, v203
	v_lshlrev_b32_e32 v202, 16, v207
	v_and_b32_e32 v203, 0xffff0000, v207
	v_lshlrev_b32_e32 v231, 16, v204
	v_and_b32_e32 v232, 0xffff0000, v204
	v_lshlrev_b32_e32 v206, 16, v208
	v_and_b32_e32 v207, 0xffff0000, v208
	v_lshlrev_b32_e32 v208, 16, v205
	v_and_b32_e32 v233, 0xffff0000, v205
	v_lshlrev_b32_e32 v204, 16, v209
	v_and_b32_e32 v205, 0xffff0000, v209
	v_lshlrev_b32_e32 v209, 16, v210
	v_max_f32_e32 v228, v228, v228
	v_max_f32_e32 v229, v229, v229
	v_max_f32_e32 v230, v230, v230
	v_max_f32_e32 v231, v231, v231
	v_max_f32_e32 v232, v232, v232
	v_max_f32_e32 v208, v208, v208
	v_max_f32_e32 v233, v233, v233
	v_max_f32_e32 v209, v209, v209
	v_max_f32_e32 v228, 0x1e3ce508, v228
	v_max_f32_e32 v229, 0x1e3ce508, v229
	v_max_f32_e32 v230, 0x1e3ce508, v230
	v_max_f32_e32 v231, 0x1e3ce508, v231
	v_max_f32_e32 v232, 0x1e3ce508, v232
	v_max_f32_e32 v234, 0x1e3ce508, v208
	v_max_f32_e32 v233, 0x1e3ce508, v233
	v_max_f32_e32 v201, v201, v201
	v_max_f32_e32 v235, 0x1e3ce508, v209
	v_rcp_f32_e32 v209, v228
	v_rcp_f32_e32 v228, v229
	v_rcp_f32_e32 v229, v230
	v_rcp_f32_e32 v230, v231
	v_rcp_f32_e32 v231, v232
	v_rcp_f32_e32 v232, v234
	v_rcp_f32_e32 v233, v233
	v_max_f32_e32 v201, 0x1e3ce508, v201
	v_rcp_f32_e32 v208, v201
	v_lshlrev_b32_e32 v201, 16, v211
	v_and_b32_e32 v210, 0xffff0000, v210
	v_max_f32_e32 v201, v201, v201
	v_max_f32_e32 v210, v210, v210
	v_pk_mul_f32 v[204:205], v[232:233], v[204:205]
	v_max_f32_e32 v201, 0x1e3ce508, v201
	v_max_f32_e32 v210, 0x1e3ce508, v210
	v_pk_mul_f32 v[124:125], v[124:125], v[204:205]
	v_rcp_f32_e32 v204, v201
	v_and_b32_e32 v201, 0xffff0000, v211
	v_rcp_f32_e32 v234, v235
	v_rcp_f32_e32 v235, v210
	v_max_f32_e32 v201, v201, v201
	v_max_f32_e32 v201, 0x1e3ce508, v201
	v_pk_mul_f32 v[202:203], v[228:229], v[202:203]
	v_rcp_f32_e32 v205, v201
	v_pk_mul_f32 v[128:129], v[128:129], v[202:203]
	v_lshlrev_b32_e32 v202, 16, v214
	v_and_b32_e32 v203, 0xffff0000, v214
	v_lshlrev_b32_e32 v201, 16, v212
	v_pk_mul_f32 v[202:203], v[234:235], v[202:203]
	v_max_f32_e32 v201, v201, v201
	v_pk_mul_f32 v[118:119], v[118:119], v[202:203]
	v_lshlrev_b32_e32 v202, 16, v215
	v_and_b32_e32 v203, 0xffff0000, v215
	v_max_f32_e32 v201, 0x1e3ce508, v201
	v_pk_mul_f32 v[202:203], v[204:205], v[202:203]
	v_rcp_f32_e32 v204, v201
	v_and_b32_e32 v201, 0xffff0000, v212
	v_max_f32_e32 v201, v201, v201
	v_max_f32_e32 v201, 0x1e3ce508, v201
	v_rcp_f32_e32 v205, v201
	v_lshlrev_b32_e32 v201, 16, v213
	v_max_f32_e32 v201, v201, v201
	v_pk_mul_f32 v[120:121], v[120:121], v[202:203]
	v_lshlrev_b32_e32 v202, 16, v216
	v_and_b32_e32 v203, 0xffff0000, v216
	v_max_f32_e32 v201, 0x1e3ce508, v201
	v_pk_mul_f32 v[202:203], v[204:205], v[202:203]
	v_rcp_f32_e32 v204, v201
	v_and_b32_e32 v201, 0xffff0000, v213
	v_max_f32_e32 v201, v201, v201
	v_max_f32_e32 v201, 0x1e3ce508, v201
	v_rcp_f32_e32 v205, v201
	v_lshlrev_b32_e32 v201, 16, v222
	v_max_f32_e32 v201, v201, v201
	v_pk_mul_f32 v[114:115], v[114:115], v[202:203]
	v_lshlrev_b32_e32 v202, 16, v217
	v_and_b32_e32 v203, 0xffff0000, v217
	v_max_f32_e32 v201, 0x1e3ce508, v201
	v_pk_mul_f32 v[202:203], v[204:205], v[202:203]
	v_rcp_f32_e32 v204, v201
	v_and_b32_e32 v201, 0xffff0000, v222
	v_max_f32_e32 v201, v201, v201
	v_max_f32_e32 v201, 0x1e3ce508, v201
	v_rcp_f32_e32 v205, v201
	v_lshlrev_b32_e32 v201, 16, v223
	v_max_f32_e32 v201, v201, v201
	v_pk_mul_f32 v[116:117], v[116:117], v[202:203]
	v_lshlrev_b32_e32 v202, 16, v218
	v_and_b32_e32 v203, 0xffff0000, v218
	v_max_f32_e32 v201, 0x1e3ce508, v201
	v_pk_mul_f32 v[202:203], v[204:205], v[202:203]
	v_rcp_f32_e32 v204, v201
	v_and_b32_e32 v201, 0xffff0000, v223
	v_max_f32_e32 v201, v201, v201
	v_max_f32_e32 v201, 0x1e3ce508, v201
	v_rcp_f32_e32 v205, v201
	v_lshlrev_b32_e32 v201, 16, v224
	v_max_f32_e32 v201, v201, v201
	v_pk_mul_f32 v[110:111], v[110:111], v[202:203]
	v_lshlrev_b32_e32 v202, 16, v219
	v_and_b32_e32 v203, 0xffff0000, v219
	v_max_f32_e32 v201, 0x1e3ce508, v201
	v_pk_mul_f32 v[202:203], v[204:205], v[202:203]
	v_rcp_f32_e32 v204, v201
	v_and_b32_e32 v201, 0xffff0000, v224
	v_max_f32_e32 v201, v201, v201
	v_max_f32_e32 v201, 0x1e3ce508, v201
	v_rcp_f32_e32 v205, v201
	v_lshlrev_b32_e32 v201, 16, v225
	v_max_f32_e32 v201, v201, v201
	v_pk_mul_f32 v[112:113], v[112:113], v[202:203]
	v_lshlrev_b32_e32 v202, 16, v220
	v_and_b32_e32 v203, 0xffff0000, v220
	v_max_f32_e32 v201, 0x1e3ce508, v201
	v_pk_mul_f32 v[202:203], v[204:205], v[202:203]
	v_rcp_f32_e32 v204, v201
	v_and_b32_e32 v201, 0xffff0000, v225
	v_max_f32_e32 v201, v201, v201
	v_max_f32_e32 v201, 0x1e3ce508, v201
	v_rcp_f32_e32 v205, v201
	v_pk_mul_f32 v[106:107], v[106:107], v[202:203]
	v_lshlrev_b32_e32 v202, 16, v221
	v_and_b32_e32 v203, 0xffff0000, v221
	v_pk_mul_f32 v[202:203], v[204:205], v[202:203]
	v_lshlrev_b32_e32 v201, 16, v166
	v_and_b32_e32 v166, 0xffff0000, v166
	v_pk_mul_f32 v[108:109], v[108:109], v[202:203]
	v_lshlrev_b32_e32 v202, 16, v162
	v_and_b32_e32 v203, 0xffff0000, v162
	v_lshlrev_b32_e32 v162, 16, v167
	v_max_f32_e32 v166, v166, v166
	v_max_f32_e32 v162, v162, v162
	v_max_f32_e32 v166, 0x1e3ce508, v166
	v_max_f32_e32 v162, 0x1e3ce508, v162
	v_rcp_f32_e32 v205, v166
	v_rcp_f32_e32 v166, v162
	v_and_b32_e32 v162, 0xffff0000, v167
	v_max_f32_e32 v162, v162, v162
	v_max_f32_e32 v162, 0x1e3ce508, v162
	v_rcp_f32_e32 v167, v162
	v_lshlrev_b32_e32 v162, 16, v163
	v_and_b32_e32 v163, 0xffff0000, v163
	v_max_f32_e32 v201, v201, v201
	v_pk_mul_f32 v[162:163], v[166:167], v[162:163]
	v_lshlrev_b32_e32 v166, 16, v168
	v_and_b32_e32 v167, 0xffff0000, v168
	v_max_f32_e32 v166, v166, v166
	v_max_f32_e32 v167, v167, v167
	v_max_f32_e32 v166, 0x1e3ce508, v166
	v_max_f32_e32 v167, 0x1e3ce508, v167
	v_rcp_f32_e32 v166, v166
	v_rcp_f32_e32 v167, v167
	v_pk_mul_f32 v[104:105], v[104:105], v[162:163]
	v_lshlrev_b32_e32 v162, 16, v164
	v_and_b32_e32 v163, 0xffff0000, v164
	v_lshlrev_b32_e32 v164, 16, v169
	v_max_f32_e32 v164, v164, v164
	v_max_f32_e32 v164, 0x1e3ce508, v164
	v_pk_mul_f32 v[162:163], v[166:167], v[162:163]
	v_rcp_f32_e32 v166, v164
	v_and_b32_e32 v164, 0xffff0000, v169
	v_max_f32_e32 v164, v164, v164
	v_max_f32_e32 v164, 0x1e3ce508, v164
	v_rcp_f32_e32 v167, v164
	v_pk_mul_f32 v[98:99], v[98:99], v[162:163]
	v_lshlrev_b32_e32 v162, 16, v165
	v_and_b32_e32 v163, 0xffff0000, v165
	v_pk_mul_f32 v[162:163], v[166:167], v[162:163]
	v_lshlrev_b32_e32 v164, 16, v158
	v_and_b32_e32 v158, 0xffff0000, v158
	v_pk_mul_f32 v[100:101], v[100:101], v[162:163]
	v_lshlrev_b32_e32 v162, 16, v154
	v_and_b32_e32 v163, 0xffff0000, v154
	v_lshlrev_b32_e32 v154, 16, v159
	v_max_f32_e32 v158, v158, v158
	v_max_f32_e32 v154, v154, v154
	v_max_f32_e32 v158, 0x1e3ce508, v158
	v_max_f32_e32 v154, 0x1e3ce508, v154
	v_rcp_f32_e32 v165, v158
	v_rcp_f32_e32 v158, v154
	v_and_b32_e32 v154, 0xffff0000, v159
	v_max_f32_e32 v154, v154, v154
	v_max_f32_e32 v154, 0x1e3ce508, v154
	v_rcp_f32_e32 v159, v154
	v_lshlrev_b32_e32 v154, 16, v155
	v_and_b32_e32 v155, 0xffff0000, v155
	v_max_f32_e32 v201, 0x1e3ce508, v201
	v_pk_mul_f32 v[154:155], v[158:159], v[154:155]
	v_lshlrev_b32_e32 v158, 16, v160
	v_and_b32_e32 v159, 0xffff0000, v160
	v_max_f32_e32 v158, v158, v158
	v_max_f32_e32 v159, v159, v159
	v_max_f32_e32 v158, 0x1e3ce508, v158
	v_max_f32_e32 v159, 0x1e3ce508, v159
	v_rcp_f32_e32 v158, v158
	v_rcp_f32_e32 v159, v159
	v_pk_mul_f32 v[96:97], v[96:97], v[154:155]
	v_lshlrev_b32_e32 v154, 16, v156
	v_and_b32_e32 v155, 0xffff0000, v156
	v_lshlrev_b32_e32 v156, 16, v161
	v_max_f32_e32 v156, v156, v156
	v_max_f32_e32 v156, 0x1e3ce508, v156
	v_pk_mul_f32 v[154:155], v[158:159], v[154:155]
	v_rcp_f32_e32 v158, v156
	v_and_b32_e32 v156, 0xffff0000, v161
	v_max_f32_e32 v156, v156, v156
	v_max_f32_e32 v156, 0x1e3ce508, v156
	v_rcp_f32_e32 v159, v156
	v_pk_mul_f32 v[90:91], v[90:91], v[154:155]
	v_lshlrev_b32_e32 v154, 16, v157
	v_and_b32_e32 v155, 0xffff0000, v157
	v_pk_mul_f32 v[154:155], v[158:159], v[154:155]
	v_lshlrev_b32_e32 v156, 16, v150
	v_and_b32_e32 v150, 0xffff0000, v150
	v_pk_mul_f32 v[92:93], v[92:93], v[154:155]
	v_lshlrev_b32_e32 v154, 16, v146
	v_and_b32_e32 v155, 0xffff0000, v146
	v_lshlrev_b32_e32 v146, 16, v151
	v_max_f32_e32 v150, v150, v150
	v_max_f32_e32 v146, v146, v146
	v_max_f32_e32 v150, 0x1e3ce508, v150
	v_max_f32_e32 v146, 0x1e3ce508, v146
	v_rcp_f32_e32 v157, v150
	v_rcp_f32_e32 v150, v146
	v_and_b32_e32 v146, 0xffff0000, v151
	v_max_f32_e32 v146, v146, v146
	v_max_f32_e32 v146, 0x1e3ce508, v146
	v_rcp_f32_e32 v151, v146
	v_lshlrev_b32_e32 v146, 16, v147
	v_and_b32_e32 v147, 0xffff0000, v147
	v_rcp_f32_e32 v204, v201
	v_pk_mul_f32 v[146:147], v[150:151], v[146:147]
	v_lshlrev_b32_e32 v150, 16, v152
	v_and_b32_e32 v151, 0xffff0000, v152
	v_max_f32_e32 v150, v150, v150
	v_max_f32_e32 v151, v151, v151
	v_max_f32_e32 v150, 0x1e3ce508, v150
	v_max_f32_e32 v151, 0x1e3ce508, v151
	v_rcp_f32_e32 v150, v150
	v_rcp_f32_e32 v151, v151
	v_pk_mul_f32 v[88:89], v[88:89], v[146:147]
	v_lshlrev_b32_e32 v146, 16, v148
	v_and_b32_e32 v147, 0xffff0000, v148
	v_lshlrev_b32_e32 v148, 16, v153
	v_max_f32_e32 v148, v148, v148
	v_max_f32_e32 v148, 0x1e3ce508, v148
	v_pk_mul_f32 v[146:147], v[150:151], v[146:147]
	v_rcp_f32_e32 v150, v148
	v_and_b32_e32 v148, 0xffff0000, v153
	v_max_f32_e32 v148, v148, v148
	v_max_f32_e32 v148, 0x1e3ce508, v148
	v_rcp_f32_e32 v151, v148
	v_pk_mul_f32 v[82:83], v[82:83], v[146:147]
	v_lshlrev_b32_e32 v146, 16, v149
	v_and_b32_e32 v147, 0xffff0000, v149
	v_pk_mul_f32 v[146:147], v[150:151], v[146:147]
	v_lshlrev_b32_e32 v148, 16, v142
	v_and_b32_e32 v142, 0xffff0000, v142
	v_pk_mul_f32 v[84:85], v[84:85], v[146:147]
	v_lshlrev_b32_e32 v146, 16, v138
	v_and_b32_e32 v147, 0xffff0000, v138
	v_lshlrev_b32_e32 v138, 16, v143
	v_max_f32_e32 v142, v142, v142
	v_max_f32_e32 v138, v138, v138
	v_max_f32_e32 v142, 0x1e3ce508, v142
	v_max_f32_e32 v138, 0x1e3ce508, v138
	v_rcp_f32_e32 v149, v142
	v_rcp_f32_e32 v142, v138
	v_and_b32_e32 v138, 0xffff0000, v143
	v_max_f32_e32 v138, v138, v138
	v_max_f32_e32 v138, 0x1e3ce508, v138
	v_rcp_f32_e32 v143, v138
	v_lshlrev_b32_e32 v138, 16, v139
	v_and_b32_e32 v139, 0xffff0000, v139
	v_pk_mul_f32 v[202:203], v[204:205], v[202:203]
	v_pk_mul_f32 v[138:139], v[142:143], v[138:139]
	v_lshlrev_b32_e32 v142, 16, v144
	v_and_b32_e32 v143, 0xffff0000, v144
	v_max_f32_e32 v142, v142, v142
	v_max_f32_e32 v143, v143, v143
	v_max_f32_e32 v142, 0x1e3ce508, v142
	v_max_f32_e32 v143, 0x1e3ce508, v143
	v_rcp_f32_e32 v142, v142
	v_rcp_f32_e32 v143, v143
	v_pk_mul_f32 v[80:81], v[80:81], v[138:139]
	v_lshlrev_b32_e32 v138, 16, v140
	v_and_b32_e32 v139, 0xffff0000, v140
	v_lshlrev_b32_e32 v140, 16, v145
	v_max_f32_e32 v140, v140, v140
	v_max_f32_e32 v140, 0x1e3ce508, v140
	v_pk_mul_f32 v[138:139], v[142:143], v[138:139]
	v_rcp_f32_e32 v142, v140
	v_and_b32_e32 v140, 0xffff0000, v145
	v_max_f32_e32 v140, v140, v140
	v_max_f32_e32 v140, 0x1e3ce508, v140
	v_rcp_f32_e32 v143, v140
	v_pk_mul_f32 v[74:75], v[74:75], v[138:139]
	v_lshlrev_b32_e32 v138, 16, v141
	v_and_b32_e32 v139, 0xffff0000, v141
	v_pk_mul_f32 v[138:139], v[142:143], v[138:139]
	v_add_u32_e32 v143, 0x80, v189
	v_mad_i64_i32 v[140:141], s[6:7], v143, s46, v[192:193]
	v_pk_mul_f32 v[102:103], v[102:103], v[202:203]
	global_load_dwordx4 v[202:205], v[140:141], off nt
	global_load_dwordx4 v[210:213], v[140:141], off offset:256 nt
	v_pk_mul_f32 v[208:209], v[208:209], v[226:227]
	v_pk_mul_f32 v[206:207], v[230:231], v[206:207]
	v_mad_i64_i32 v[144:145], s[6:7], v143, s46, v[190:191]
	v_pk_mul_f32 v[126:127], v[126:127], v[208:209]
	v_pk_mul_f32 v[122:123], v[122:123], v[206:207]
	global_load_dwordx4 v[206:209], v[144:145], off nt
	global_load_dwordx4 v[214:217], v[144:145], off offset:256 nt
	v_lshlrev_b32_e32 v142, 16, v134
	v_and_b32_e32 v134, 0xffff0000, v134
	v_pk_mul_f32 v[76:77], v[76:77], v[138:139]
	v_lshlrev_b32_e32 v138, 16, v130
	v_and_b32_e32 v139, 0xffff0000, v130
	v_lshlrev_b32_e32 v130, 16, v135
	v_max_f32_e32 v134, v134, v134
	v_max_f32_e32 v130, v130, v130
	v_max_f32_e32 v134, 0x1e3ce508, v134
	v_max_f32_e32 v130, 0x1e3ce508, v130
	v_rcp_f32_e32 v143, v134
	v_rcp_f32_e32 v134, v130
	v_and_b32_e32 v130, 0xffff0000, v135
	v_max_f32_e32 v130, v130, v130
	v_max_f32_e32 v130, 0x1e3ce508, v130
	v_rcp_f32_e32 v135, v130
	v_lshlrev_b32_e32 v130, 16, v131
	v_and_b32_e32 v131, 0xffff0000, v131
	v_max_f32_e32 v164, v164, v164
	v_pk_mul_f32 v[130:131], v[134:135], v[130:131]
	v_lshlrev_b32_e32 v134, 16, v136
	v_and_b32_e32 v135, 0xffff0000, v136
	v_max_f32_e32 v134, v134, v134
	v_max_f32_e32 v135, v135, v135
	v_max_f32_e32 v134, 0x1e3ce508, v134
	v_max_f32_e32 v135, 0x1e3ce508, v135
	v_rcp_f32_e32 v134, v134
	v_rcp_f32_e32 v135, v135
	v_pk_mul_f32 v[72:73], v[72:73], v[130:131]
	v_lshlrev_b32_e32 v130, 16, v132
	v_and_b32_e32 v131, 0xffff0000, v132
	v_pk_mul_f32 v[130:131], v[134:135], v[130:131]
	v_max_f32_e32 v164, 0x1e3ce508, v164
	v_pk_mul_f32 v[66:67], v[66:67], v[130:131]
	v_lshlrev_b32_e32 v130, 16, v137
	v_and_b32_e32 v131, 0xffff0000, v137
	v_max_f32_e32 v130, v130, v130
	v_max_f32_e32 v131, v131, v131
	v_max_f32_e32 v130, 0x1e3ce508, v130
	v_max_f32_e32 v131, 0x1e3ce508, v131
	v_rcp_f32_e32 v130, v130
	v_rcp_f32_e32 v131, v131
	v_rcp_f32_e32 v164, v164
	v_lshlrev_b32_e32 v132, 16, v133
	v_and_b32_e32 v133, 0xffff0000, v133
	v_pk_mul_f32 v[130:131], v[130:131], v[132:133]
	v_add_u32_e32 v132, 0x90, v189
	v_pk_mul_f32 v[162:163], v[164:165], v[162:163]
	v_pk_mul_f32 v[68:69], v[68:69], v[130:131]
	v_mad_i64_i32 v[130:131], s[6:7], v132, s46, v[190:191]
	v_pk_mul_f32 v[94:95], v[94:95], v[162:163]
	v_mad_i64_i32 v[132:133], s[6:7], v132, s46, v[192:193]
	global_load_dwordx4 v[218:221], v[130:131], off nt
	global_load_dwordx4 v[162:165], v[130:131], off offset:256 nt
	global_load_dwordx4 v[222:225], v[132:133], off nt
	global_load_dwordx4 v[166:169], v[132:133], off offset:256 nt
	v_max_f32_e32 v156, v156, v156
	v_max_f32_e32 v148, v148, v148
	v_max_f32_e32 v156, 0x1e3ce508, v156
	v_max_f32_e32 v148, 0x1e3ce508, v148
	v_rcp_f32_e32 v156, v156
	v_rcp_f32_e32 v148, v148
	v_add_u32_e32 v132, 0xa0, v189
	v_mad_i64_i32 v[130:131], s[6:7], v132, s46, v[190:191]
	v_pk_mul_f32 v[154:155], v[156:157], v[154:155]
	v_pk_mul_f32 v[146:147], v[148:149], v[146:147]
	v_mad_i64_i32 v[132:133], s[6:7], v132, s46, v[192:193]
	v_pk_mul_f32 v[86:87], v[86:87], v[154:155]
	v_pk_mul_f32 v[78:79], v[78:79], v[146:147]
	global_load_dwordx4 v[154:157], v[130:131], off nt
	global_load_dwordx4 v[146:149], v[130:131], off offset:256 nt
	global_load_dwordx4 v[158:161], v[132:133], off nt
	global_load_dwordx4 v[150:153], v[132:133], off offset:256 nt
	v_add_u32_e32 v132, 0xb0, v189
	s_waitcnt vmcnt(11)
	v_lshlrev_b32_e32 v136, 16, v202
	v_lshlrev_b32_e32 v189, 16, v203
	v_max_f32_e32 v136, v136, v136
	v_max_f32_e32 v189, v189, v189
	v_max_f32_e32 v136, 0x1e3ce508, v136
	v_max_f32_e32 v189, 0x1e3ce508, v189
	v_rcp_f32_e32 v226, v136
	v_and_b32_e32 v136, 0xffff0000, v202
	v_rcp_f32_e32 v202, v189
	v_and_b32_e32 v189, 0xffff0000, v203
	v_max_f32_e32 v189, v189, v189
	v_max_f32_e32 v189, 0x1e3ce508, v189
	v_rcp_f32_e32 v203, v189
	v_lshlrev_b32_e32 v189, 16, v204
	v_max_f32_e32 v189, v189, v189
	s_waitcnt vmcnt(9)
	v_lshlrev_b32_e32 v228, 16, v206
	v_and_b32_e32 v229, 0xffff0000, v206
	v_lshlrev_b32_e32 v206, 16, v207
	v_and_b32_e32 v207, 0xffff0000, v207
	v_max_f32_e32 v189, 0x1e3ce508, v189
	v_pk_mul_f32 v[202:203], v[202:203], v[206:207]
	v_rcp_f32_e32 v206, v189
	v_and_b32_e32 v189, 0xffff0000, v204
	v_max_f32_e32 v189, v189, v189
	v_max_f32_e32 v189, 0x1e3ce508, v189
	v_rcp_f32_e32 v207, v189
	v_lshlrev_b32_e32 v189, 16, v205
	v_max_f32_e32 v189, v189, v189
	v_max_f32_e32 v189, 0x1e3ce508, v189
	v_rcp_f32_e32 v204, v189
	v_and_b32_e32 v189, 0xffff0000, v205
	v_max_f32_e32 v189, v189, v189
	v_max_f32_e32 v189, 0x1e3ce508, v189
	v_rcp_f32_e32 v205, v189
	v_pk_mul_f32 v[64:65], v[64:65], v[202:203]
	v_lshlrev_b32_e32 v202, 16, v208
	v_and_b32_e32 v203, 0xffff0000, v208
	v_lshlrev_b32_e32 v189, 16, v210
	v_pk_mul_f32 v[202:203], v[206:207], v[202:203]
	v_max_f32_e32 v189, v189, v189
	v_pk_mul_f32 v[58:59], v[58:59], v[202:203]
	v_lshlrev_b32_e32 v202, 16, v209
	v_and_b32_e32 v203, 0xffff0000, v209
	v_max_f32_e32 v189, 0x1e3ce508, v189
	v_pk_mul_f32 v[202:203], v[204:205], v[202:203]
	v_rcp_f32_e32 v204, v189
	v_and_b32_e32 v189, 0xffff0000, v210
	v_max_f32_e32 v189, v189, v189
	v_max_f32_e32 v189, 0x1e3ce508, v189
	v_rcp_f32_e32 v205, v189
	v_lshlrev_b32_e32 v189, 16, v211
	v_max_f32_e32 v189, v189, v189
	v_pk_mul_f32 v[60:61], v[60:61], v[202:203]
	s_waitcnt vmcnt(8)
	v_lshlrev_b32_e32 v202, 16, v214
	v_and_b32_e32 v203, 0xffff0000, v214
	v_max_f32_e32 v189, 0x1e3ce508, v189
	v_pk_mul_f32 v[202:203], v[204:205], v[202:203]
	v_rcp_f32_e32 v204, v189
	v_and_b32_e32 v189, 0xffff0000, v211
	v_max_f32_e32 v189, v189, v189
	v_max_f32_e32 v189, 0x1e3ce508, v189
	v_rcp_f32_e32 v205, v189
	v_lshlrev_b32_e32 v189, 16, v212
	v_max_f32_e32 v189, v189, v189
	v_pk_mul_f32 v[54:55], v[54:55], v[202:203]
	v_lshlrev_b32_e32 v202, 16, v215
	v_and_b32_e32 v203, 0xffff0000, v215
	v_max_f32_e32 v189, 0x1e3ce508, v189
	v_pk_mul_f32 v[202:203], v[204:205], v[202:203]
	v_rcp_f32_e32 v204, v189
	v_and_b32_e32 v189, 0xffff0000, v212
	v_max_f32_e32 v189, v189, v189
	v_max_f32_e32 v189, 0x1e3ce508, v189
	v_rcp_f32_e32 v205, v189
	v_lshlrev_b32_e32 v189, 16, v213
	v_max_f32_e32 v189, v189, v189
	v_pk_mul_f32 v[56:57], v[56:57], v[202:203]
	v_lshlrev_b32_e32 v202, 16, v216
	v_and_b32_e32 v203, 0xffff0000, v216
	v_max_f32_e32 v189, 0x1e3ce508, v189
	v_pk_mul_f32 v[202:203], v[204:205], v[202:203]
	v_rcp_f32_e32 v204, v189
	v_and_b32_e32 v189, 0xffff0000, v213
	v_max_f32_e32 v189, v189, v189
	v_max_f32_e32 v189, 0x1e3ce508, v189
	v_rcp_f32_e32 v205, v189
	s_waitcnt vmcnt(5)
	v_lshlrev_b32_e32 v189, 16, v222
	v_max_f32_e32 v189, v189, v189
	v_pk_mul_f32 v[50:51], v[50:51], v[202:203]
	v_lshlrev_b32_e32 v202, 16, v217
	v_and_b32_e32 v203, 0xffff0000, v217
	v_max_f32_e32 v189, 0x1e3ce508, v189
	v_pk_mul_f32 v[202:203], v[204:205], v[202:203]
	v_rcp_f32_e32 v204, v189
	v_and_b32_e32 v189, 0xffff0000, v222
	v_max_f32_e32 v189, v189, v189
	v_max_f32_e32 v189, 0x1e3ce508, v189
	v_rcp_f32_e32 v205, v189
	v_lshlrev_b32_e32 v189, 16, v223
	v_max_f32_e32 v189, v189, v189
	v_pk_mul_f32 v[52:53], v[52:53], v[202:203]
	v_lshlrev_b32_e32 v202, 16, v218
	v_and_b32_e32 v203, 0xffff0000, v218
	v_max_f32_e32 v189, 0x1e3ce508, v189
	v_pk_mul_f32 v[202:203], v[204:205], v[202:203]
	v_rcp_f32_e32 v204, v189
	v_and_b32_e32 v189, 0xffff0000, v223
	v_max_f32_e32 v189, v189, v189
	v_max_f32_e32 v189, 0x1e3ce508, v189
	v_rcp_f32_e32 v205, v189
	v_lshlrev_b32_e32 v189, 16, v224
	v_max_f32_e32 v189, v189, v189
	v_pk_mul_f32 v[46:47], v[46:47], v[202:203]
	v_lshlrev_b32_e32 v202, 16, v219
	v_and_b32_e32 v203, 0xffff0000, v219
	v_max_f32_e32 v189, 0x1e3ce508, v189
	v_pk_mul_f32 v[202:203], v[204:205], v[202:203]
	v_rcp_f32_e32 v204, v189
	v_and_b32_e32 v189, 0xffff0000, v224
	v_max_f32_e32 v189, v189, v189
	v_max_f32_e32 v189, 0x1e3ce508, v189
	v_rcp_f32_e32 v205, v189
	v_max_f32_e32 v142, v142, v142
	v_lshlrev_b32_e32 v189, 16, v225
	v_max_f32_e32 v142, 0x1e3ce508, v142
	v_max_f32_e32 v189, v189, v189
	v_rcp_f32_e32 v142, v142
	v_pk_mul_f32 v[48:49], v[48:49], v[202:203]
	v_lshlrev_b32_e32 v202, 16, v220
	v_and_b32_e32 v203, 0xffff0000, v220
	v_max_f32_e32 v189, 0x1e3ce508, v189
	v_pk_mul_f32 v[202:203], v[204:205], v[202:203]
	v_rcp_f32_e32 v204, v189
	v_and_b32_e32 v189, 0xffff0000, v225
	v_max_f32_e32 v189, v189, v189
	v_max_f32_e32 v136, v136, v136
	v_max_f32_e32 v189, 0x1e3ce508, v189
	v_pk_mul_f32 v[138:139], v[142:143], v[138:139]
	v_mad_i64_i32 v[130:131], s[6:7], v132, s46, v[190:191]
	v_mad_i64_i32 v[134:135], s[6:7], v132, s46, v[192:193]
	v_max_f32_e32 v136, 0x1e3ce508, v136
	v_rcp_f32_e32 v205, v189
	v_pk_mul_f32 v[70:71], v[70:71], v[138:139]
	global_load_dwordx4 v[138:141], v[130:131], off nt
	s_nop 0
	global_load_dwordx4 v[130:133], v[130:131], off offset:256 nt
	v_rcp_f32_e32 v227, v136
	global_load_dwordx4 v[142:145], v[134:135], off nt
	s_nop 0
	global_load_dwordx4 v[134:137], v[134:135], off offset:256 nt
	v_pk_mul_f32 v[42:43], v[42:43], v[202:203]
	v_lshlrev_b32_e32 v202, 16, v221
	v_and_b32_e32 v203, 0xffff0000, v221
	v_pk_mul_f32 v[202:203], v[204:205], v[202:203]
	s_waitcnt vmcnt(8)
	v_lshlrev_b32_e32 v189, 16, v166
	v_and_b32_e32 v166, 0xffff0000, v166
	v_pk_mul_f32 v[44:45], v[44:45], v[202:203]
	v_lshlrev_b32_e32 v202, 16, v162
	v_and_b32_e32 v203, 0xffff0000, v162
	v_lshlrev_b32_e32 v162, 16, v167
	v_max_f32_e32 v166, v166, v166
	v_max_f32_e32 v162, v162, v162
	v_max_f32_e32 v166, 0x1e3ce508, v166
	v_max_f32_e32 v162, 0x1e3ce508, v162
	v_rcp_f32_e32 v205, v166
	v_rcp_f32_e32 v166, v162
	v_and_b32_e32 v162, 0xffff0000, v167
	v_max_f32_e32 v162, v162, v162
	v_max_f32_e32 v162, 0x1e3ce508, v162
	v_rcp_f32_e32 v167, v162
	v_lshlrev_b32_e32 v162, 16, v163
	v_and_b32_e32 v163, 0xffff0000, v163
	v_max_f32_e32 v189, v189, v189
	v_pk_mul_f32 v[162:163], v[166:167], v[162:163]
	v_lshlrev_b32_e32 v166, 16, v168
	v_and_b32_e32 v167, 0xffff0000, v168
	v_max_f32_e32 v166, v166, v166
	v_max_f32_e32 v167, v167, v167
	v_max_f32_e32 v166, 0x1e3ce508, v166
	v_max_f32_e32 v167, 0x1e3ce508, v167
	v_rcp_f32_e32 v166, v166
	v_rcp_f32_e32 v167, v167
	v_pk_mul_f32 v[40:41], v[40:41], v[162:163]
	v_lshlrev_b32_e32 v162, 16, v164
	v_and_b32_e32 v163, 0xffff0000, v164
	v_lshlrev_b32_e32 v164, 16, v169
	v_max_f32_e32 v164, v164, v164
	v_max_f32_e32 v164, 0x1e3ce508, v164
	v_pk_mul_f32 v[162:163], v[166:167], v[162:163]
	v_rcp_f32_e32 v166, v164
	v_and_b32_e32 v164, 0xffff0000, v169
	v_max_f32_e32 v164, v164, v164
	v_max_f32_e32 v164, 0x1e3ce508, v164
	v_rcp_f32_e32 v167, v164
	v_pk_mul_f32 v[34:35], v[34:35], v[162:163]
	v_lshlrev_b32_e32 v162, 16, v165
	v_and_b32_e32 v163, 0xffff0000, v165
	v_pk_mul_f32 v[162:163], v[166:167], v[162:163]
	s_waitcnt vmcnt(5)
	v_lshlrev_b32_e32 v164, 16, v158
	v_and_b32_e32 v158, 0xffff0000, v158
	v_pk_mul_f32 v[36:37], v[36:37], v[162:163]
	v_lshlrev_b32_e32 v162, 16, v154
	v_and_b32_e32 v163, 0xffff0000, v154
	v_lshlrev_b32_e32 v154, 16, v159
	v_max_f32_e32 v158, v158, v158
	v_max_f32_e32 v154, v154, v154
	v_max_f32_e32 v158, 0x1e3ce508, v158
	v_max_f32_e32 v154, 0x1e3ce508, v154
	v_rcp_f32_e32 v165, v158
	v_rcp_f32_e32 v158, v154
	v_and_b32_e32 v154, 0xffff0000, v159
	v_max_f32_e32 v154, v154, v154
	v_max_f32_e32 v154, 0x1e3ce508, v154
	v_rcp_f32_e32 v159, v154
	v_lshlrev_b32_e32 v154, 16, v155
	v_and_b32_e32 v155, 0xffff0000, v155
	v_max_f32_e32 v164, v164, v164
	v_pk_mul_f32 v[154:155], v[158:159], v[154:155]
	v_lshlrev_b32_e32 v158, 16, v160
	v_and_b32_e32 v159, 0xffff0000, v160
	v_max_f32_e32 v158, v158, v158
	v_max_f32_e32 v159, v159, v159
	v_max_f32_e32 v158, 0x1e3ce508, v158
	v_max_f32_e32 v159, 0x1e3ce508, v159
	v_rcp_f32_e32 v158, v158
	v_rcp_f32_e32 v159, v159
	v_pk_mul_f32 v[32:33], v[32:33], v[154:155]
	v_lshlrev_b32_e32 v154, 16, v156
	v_and_b32_e32 v155, 0xffff0000, v156
	v_lshlrev_b32_e32 v156, 16, v161
	v_max_f32_e32 v156, v156, v156
	v_max_f32_e32 v156, 0x1e3ce508, v156
	v_pk_mul_f32 v[154:155], v[158:159], v[154:155]
	v_rcp_f32_e32 v158, v156
	v_and_b32_e32 v156, 0xffff0000, v161
	v_max_f32_e32 v156, v156, v156
	v_max_f32_e32 v156, 0x1e3ce508, v156
	v_rcp_f32_e32 v159, v156
	v_pk_mul_f32 v[26:27], v[26:27], v[154:155]
	v_lshlrev_b32_e32 v154, 16, v157
	v_and_b32_e32 v155, 0xffff0000, v157
	v_pk_mul_f32 v[154:155], v[158:159], v[154:155]
	s_waitcnt vmcnt(4)
	v_lshlrev_b32_e32 v156, 16, v150
	v_and_b32_e32 v150, 0xffff0000, v150
	v_pk_mul_f32 v[28:29], v[28:29], v[154:155]
	v_lshlrev_b32_e32 v154, 16, v146
	v_and_b32_e32 v155, 0xffff0000, v146
	v_lshlrev_b32_e32 v146, 16, v151
	v_max_f32_e32 v150, v150, v150
	v_max_f32_e32 v146, v146, v146
	v_max_f32_e32 v150, 0x1e3ce508, v150
	v_max_f32_e32 v146, 0x1e3ce508, v146
	v_rcp_f32_e32 v157, v150
	v_rcp_f32_e32 v150, v146
	v_and_b32_e32 v146, 0xffff0000, v151
	v_max_f32_e32 v146, v146, v146
	v_max_f32_e32 v146, 0x1e3ce508, v146
	v_rcp_f32_e32 v151, v146
	v_lshlrev_b32_e32 v146, 16, v147
	v_and_b32_e32 v147, 0xffff0000, v147
	v_max_f32_e32 v156, v156, v156
	v_pk_mul_f32 v[146:147], v[150:151], v[146:147]
	v_lshlrev_b32_e32 v150, 16, v152
	v_and_b32_e32 v151, 0xffff0000, v152
	v_max_f32_e32 v150, v150, v150
	v_max_f32_e32 v151, v151, v151
	v_max_f32_e32 v150, 0x1e3ce508, v150
	v_max_f32_e32 v151, 0x1e3ce508, v151
	v_rcp_f32_e32 v150, v150
	v_rcp_f32_e32 v151, v151
	v_pk_mul_f32 v[24:25], v[24:25], v[146:147]
	v_lshlrev_b32_e32 v146, 16, v148
	v_and_b32_e32 v147, 0xffff0000, v148
	v_lshlrev_b32_e32 v148, 16, v153
	v_max_f32_e32 v148, v148, v148
	v_max_f32_e32 v148, 0x1e3ce508, v148
	v_pk_mul_f32 v[146:147], v[150:151], v[146:147]
	v_rcp_f32_e32 v150, v148
	v_and_b32_e32 v148, 0xffff0000, v153
	v_max_f32_e32 v148, v148, v148
	v_max_f32_e32 v148, 0x1e3ce508, v148
	v_rcp_f32_e32 v151, v148
	v_pk_mul_f32 v[18:19], v[18:19], v[146:147]
	v_lshlrev_b32_e32 v146, 16, v149
	v_and_b32_e32 v147, 0xffff0000, v149
	v_pk_mul_f32 v[146:147], v[150:151], v[146:147]
	s_waitcnt vmcnt(1)
	v_lshlrev_b32_e32 v148, 16, v142
	v_and_b32_e32 v142, 0xffff0000, v142
	v_pk_mul_f32 v[20:21], v[20:21], v[146:147]
	v_lshlrev_b32_e32 v146, 16, v138
	v_and_b32_e32 v147, 0xffff0000, v138
	v_lshlrev_b32_e32 v138, 16, v143
	v_max_f32_e32 v142, v142, v142
	v_max_f32_e32 v138, v138, v138
	v_max_f32_e32 v142, 0x1e3ce508, v142
	v_max_f32_e32 v138, 0x1e3ce508, v138
	v_rcp_f32_e32 v149, v142
	v_rcp_f32_e32 v142, v138
	v_and_b32_e32 v138, 0xffff0000, v143
	v_max_f32_e32 v138, v138, v138
	v_max_f32_e32 v138, 0x1e3ce508, v138
	v_rcp_f32_e32 v143, v138
	v_lshlrev_b32_e32 v138, 16, v139
	v_and_b32_e32 v139, 0xffff0000, v139
	v_max_f32_e32 v148, v148, v148
	v_pk_mul_f32 v[138:139], v[142:143], v[138:139]
	v_lshlrev_b32_e32 v142, 16, v144
	v_and_b32_e32 v143, 0xffff0000, v144
	v_max_f32_e32 v142, v142, v142
	v_max_f32_e32 v143, v143, v143
	v_max_f32_e32 v142, 0x1e3ce508, v142
	v_max_f32_e32 v143, 0x1e3ce508, v143
	v_rcp_f32_e32 v142, v142
	v_rcp_f32_e32 v143, v143
	v_pk_mul_f32 v[16:17], v[16:17], v[138:139]
	v_lshlrev_b32_e32 v138, 16, v140
	v_and_b32_e32 v139, 0xffff0000, v140
	v_lshlrev_b32_e32 v140, 16, v145
	v_max_f32_e32 v140, v140, v140
	v_max_f32_e32 v140, 0x1e3ce508, v140
	v_pk_mul_f32 v[138:139], v[142:143], v[138:139]
	v_rcp_f32_e32 v142, v140
	v_and_b32_e32 v140, 0xffff0000, v145
	v_max_f32_e32 v140, v140, v140
	v_max_f32_e32 v140, 0x1e3ce508, v140
	v_rcp_f32_e32 v143, v140
	v_pk_mul_f32 v[10:11], v[10:11], v[138:139]
	v_lshlrev_b32_e32 v138, 16, v141
	v_and_b32_e32 v139, 0xffff0000, v141
	v_pk_mul_f32 v[138:139], v[142:143], v[138:139]
	s_waitcnt vmcnt(0)
	v_lshlrev_b32_e32 v140, 16, v134
	v_and_b32_e32 v134, 0xffff0000, v134
	v_pk_mul_f32 v[12:13], v[12:13], v[138:139]
	v_lshlrev_b32_e32 v138, 16, v130
	v_and_b32_e32 v139, 0xffff0000, v130
	v_lshlrev_b32_e32 v130, 16, v135
	v_max_f32_e32 v134, v134, v134
	v_max_f32_e32 v130, v130, v130
	v_max_f32_e32 v134, 0x1e3ce508, v134
	v_max_f32_e32 v130, 0x1e3ce508, v130
	v_rcp_f32_e32 v141, v134
	v_rcp_f32_e32 v134, v130
	v_and_b32_e32 v130, 0xffff0000, v135
	v_max_f32_e32 v130, v130, v130
	v_max_f32_e32 v130, 0x1e3ce508, v130
	v_rcp_f32_e32 v135, v130
	v_lshlrev_b32_e32 v130, 16, v131
	v_and_b32_e32 v131, 0xffff0000, v131
	v_max_f32_e32 v140, v140, v140
	v_pk_mul_f32 v[130:131], v[134:135], v[130:131]
	v_lshlrev_b32_e32 v134, 16, v136
	v_and_b32_e32 v135, 0xffff0000, v136
	v_max_f32_e32 v134, v134, v134
	v_max_f32_e32 v135, v135, v135
	v_max_f32_e32 v134, 0x1e3ce508, v134
	v_max_f32_e32 v135, 0x1e3ce508, v135
	v_rcp_f32_e32 v134, v134
	v_rcp_f32_e32 v135, v135
	v_pk_mul_f32 v[8:9], v[8:9], v[130:131]
	v_lshlrev_b32_e32 v130, 16, v132
	v_and_b32_e32 v131, 0xffff0000, v132
	v_lshlrev_b32_e32 v132, 16, v137
	v_max_f32_e32 v132, v132, v132
	v_max_f32_e32 v132, 0x1e3ce508, v132
	v_pk_mul_f32 v[130:131], v[134:135], v[130:131]
	v_rcp_f32_e32 v134, v132
	v_and_b32_e32 v132, 0xffff0000, v137
	v_max_f32_e32 v132, v132, v132
	v_max_f32_e32 v189, 0x1e3ce508, v189
	v_max_f32_e32 v164, 0x1e3ce508, v164
	v_max_f32_e32 v156, 0x1e3ce508, v156
	v_max_f32_e32 v148, 0x1e3ce508, v148
	v_max_f32_e32 v140, 0x1e3ce508, v140
	v_max_f32_e32 v132, 0x1e3ce508, v132
	v_rcp_f32_e32 v204, v189
	v_rcp_f32_e32 v164, v164
	v_rcp_f32_e32 v156, v156
	v_rcp_f32_e32 v148, v148
	v_rcp_f32_e32 v140, v140
	v_rcp_f32_e32 v135, v132
	v_pk_mul_f32 v[2:3], v[2:3], v[130:131]
	v_lshlrev_b32_e32 v130, 16, v133
	v_and_b32_e32 v131, 0xffff0000, v133
	v_pk_mul_f32 v[226:227], v[226:227], v[228:229]
	v_pk_mul_f32 v[202:203], v[204:205], v[202:203]
	v_pk_mul_f32 v[162:163], v[164:165], v[162:163]
	v_pk_mul_f32 v[154:155], v[156:157], v[154:155]
	v_pk_mul_f32 v[146:147], v[148:149], v[146:147]
	v_pk_mul_f32 v[138:139], v[140:141], v[138:139]
	v_pk_mul_f32 v[130:131], v[134:135], v[130:131]
	v_pk_mul_f32 v[62:63], v[62:63], v[226:227]
	v_pk_mul_f32 v[38:39], v[38:39], v[202:203]
	v_pk_mul_f32 v[30:31], v[30:31], v[162:163]
	v_pk_mul_f32 v[22:23], v[22:23], v[154:155]
	v_pk_mul_f32 v[14:15], v[14:15], v[146:147]
	v_pk_mul_f32 v[6:7], v[6:7], v[138:139]
	v_pk_mul_f32 v[4:5], v[4:5], v[130:131]
	s_branch .LBB0_901

.LBB0_906:
	v_mov_b64_e32 v[130:131], s[12:13]
	v_mad_i64_i32 v[132:133], s[6:7], v188, s46, v[130:131]
	v_lshl_add_u64 v[136:137], v[132:133], 0, v[186:187]
	global_load_dwordx4 v[132:135], v[136:137], off nt
	v_ashrrev_i32_e32 v189, 31, v188
	s_andn2_b64 vcc, exec, s[2:3]
	s_mov_b64 s[2:3], -1
	s_waitcnt vmcnt(0)
	v_lshlrev_b32_e32 v138, 16, v132
	v_and_b32_e32 v132, 0xffff0000, v132
	v_lshlrev_b32_e32 v139, 16, v133
	v_and_b32_e32 v133, 0xffff0000, v133
	v_lshlrev_b32_e32 v140, 16, v134
	v_and_b32_e32 v134, 0xffff0000, v134
	v_lshlrev_b32_e32 v141, 16, v135
	v_and_b32_e32 v135, 0xffff0000, v135
	v_max_f32_e32 v138, v138, v138
	v_max_f32_e32 v140, v140, v140
	v_max_f32_e32 v142, v132, v132
	v_max_f32_e32 v143, v134, v134
	v_max_f32_e32 v139, v139, v139
	v_max_f32_e32 v141, v141, v141
	v_max_f32_e32 v144, v133, v133
	v_max_f32_e32 v145, v135, v135
	v_max_f32_e32 v132, 0x1e3ce508, v138
	v_max_f32_e32 v134, 0x1e3ce508, v140
	v_max_f32_e32 v133, 0x1e3ce508, v142
	v_max_f32_e32 v135, 0x1e3ce508, v143
	v_max_f32_e32 v138, 0x1e3ce508, v139
	v_max_f32_e32 v140, 0x1e3ce508, v141
	v_max_f32_e32 v139, 0x1e3ce508, v144
	v_max_f32_e32 v141, 0x1e3ce508, v145
	v_pk_mul_f32 v[128:129], v[128:129], v[138:139]
	v_pk_mul_f32 v[126:127], v[126:127], v[132:133]
	v_pk_mul_f32 v[132:133], v[124:125], v[140:141]
	v_pk_mul_f32 v[124:125], v[122:123], v[134:135]
	v_cvt_pk_bf16_f32 v122, v126, v127
	v_cvt_pk_bf16_f32 v123, v128, v129
	v_lshlrev_b64 v[134:135], 12, v[188:189]
	v_cvt_pk_bf16_f32 v124, v124, v125
	v_cvt_pk_bf16_f32 v125, v132, v133
	global_load_dwordx4 v[126:129], v[136:137], off offset:256 nt
	v_lshl_add_u64 v[134:135], s[4:5], 0, v[134:135]
	v_lshl_add_u64 v[134:135], v[134:135], 0, v[186:187]
	global_store_dwordx4 v[134:135], v[122:125], off
	v_or_b32_e32 v132, 16, v188
	v_mad_i64_i32 v[136:137], s[6:7], v132, s46, v[130:131]
	v_lshl_add_u64 v[136:137], v[136:137], 0, v[186:187]
	s_waitcnt vmcnt(1)
	v_lshlrev_b32_e32 v122, 16, v126
	v_and_b32_e32 v123, 0xffff0000, v126
	v_lshlrev_b32_e32 v124, 16, v127
	v_and_b32_e32 v125, 0xffff0000, v127
	v_lshlrev_b32_e32 v126, 16, v128
	v_and_b32_e32 v127, 0xffff0000, v128
	v_lshlrev_b32_e32 v128, 16, v129
	v_and_b32_e32 v129, 0xffff0000, v129
	v_max_f32_e32 v122, v122, v122
	v_max_f32_e32 v126, v126, v126
	v_max_f32_e32 v123, v123, v123
	v_max_f32_e32 v127, v127, v127
	v_max_f32_e32 v133, v124, v124
	v_max_f32_e32 v128, v128, v128
	v_max_f32_e32 v138, v125, v125
	v_max_f32_e32 v129, v129, v129
	v_max_f32_e32 v122, 0x1e3ce508, v122
	v_max_f32_e32 v124, 0x1e3ce508, v126
	v_max_f32_e32 v123, 0x1e3ce508, v123
	v_max_f32_e32 v125, 0x1e3ce508, v127
	v_max_f32_e32 v126, 0x1e3ce508, v133
	v_max_f32_e32 v128, 0x1e3ce508, v128
	v_max_f32_e32 v127, 0x1e3ce508, v138
	v_max_f32_e32 v129, 0x1e3ce508, v129
	v_pk_mul_f32 v[120:121], v[120:121], v[126:127]
	v_pk_mul_f32 v[118:119], v[118:119], v[122:123]
	v_pk_mul_f32 v[122:123], v[116:117], v[128:129]
	v_pk_mul_f32 v[116:117], v[114:115], v[124:125]
	v_cvt_pk_bf16_f32 v114, v118, v119
	v_cvt_pk_bf16_f32 v115, v120, v121
	v_ashrrev_i32_e32 v133, 31, v132
	v_cvt_pk_bf16_f32 v116, v116, v117
	v_cvt_pk_bf16_f32 v117, v122, v123
	global_load_dwordx4 v[118:121], v[136:137], off nt
	s_nop 0
	global_store_dwordx4 v[134:135], v[114:117], off offset:256
	s_waitcnt vmcnt(1)
	s_nop 0
	v_lshlrev_b32_e32 v114, 16, v118
	v_and_b32_e32 v115, 0xffff0000, v118
	v_lshlrev_b32_e32 v116, 16, v119
	v_and_b32_e32 v117, 0xffff0000, v119
	v_lshlrev_b32_e32 v118, 16, v120
	v_and_b32_e32 v119, 0xffff0000, v120
	v_lshlrev_b32_e32 v120, 16, v121
	v_and_b32_e32 v121, 0xffff0000, v121
	v_max_f32_e32 v114, v114, v114
	v_max_f32_e32 v118, v118, v118
	v_max_f32_e32 v115, v115, v115
	v_max_f32_e32 v119, v119, v119
	v_max_f32_e32 v122, v116, v116
	v_max_f32_e32 v120, v120, v120
	v_max_f32_e32 v123, v117, v117
	v_max_f32_e32 v121, v121, v121
	v_max_f32_e32 v114, 0x1e3ce508, v114
	v_max_f32_e32 v116, 0x1e3ce508, v118
	v_max_f32_e32 v115, 0x1e3ce508, v115
	v_max_f32_e32 v117, 0x1e3ce508, v119
	v_max_f32_e32 v118, 0x1e3ce508, v122
	v_max_f32_e32 v120, 0x1e3ce508, v120
	v_max_f32_e32 v119, 0x1e3ce508, v123
	v_max_f32_e32 v121, 0x1e3ce508, v121
	v_pk_mul_f32 v[112:113], v[112:113], v[118:119]
	v_pk_mul_f32 v[110:111], v[110:111], v[114:115]
	v_pk_mul_f32 v[114:115], v[108:109], v[120:121]
	v_pk_mul_f32 v[108:109], v[106:107], v[116:117]
	v_cvt_pk_bf16_f32 v106, v110, v111
	v_cvt_pk_bf16_f32 v107, v112, v113
	v_lshlrev_b64 v[118:119], 12, v[132:133]
	v_cvt_pk_bf16_f32 v108, v108, v109
	v_cvt_pk_bf16_f32 v109, v114, v115
	global_load_dwordx4 v[110:113], v[136:137], off offset:256 nt
	v_lshl_add_u64 v[118:119], s[4:5], 0, v[118:119]
	v_lshl_add_u64 v[118:119], v[118:119], 0, v[186:187]
	global_store_dwordx4 v[118:119], v[106:109], off
	v_or_b32_e32 v114, 32, v188
	v_mad_i64_i32 v[116:117], s[6:7], v114, s46, v[130:131]
	v_lshl_add_u64 v[116:117], v[116:117], 0, v[186:187]
	s_waitcnt vmcnt(1)
	v_lshlrev_b32_e32 v106, 16, v110
	v_and_b32_e32 v107, 0xffff0000, v110
	v_lshlrev_b32_e32 v108, 16, v111
	v_and_b32_e32 v109, 0xffff0000, v111
	v_lshlrev_b32_e32 v110, 16, v112
	v_and_b32_e32 v111, 0xffff0000, v112
	v_lshlrev_b32_e32 v112, 16, v113
	v_and_b32_e32 v113, 0xffff0000, v113
	v_max_f32_e32 v106, v106, v106
	v_max_f32_e32 v110, v110, v110
	v_max_f32_e32 v107, v107, v107
	v_max_f32_e32 v111, v111, v111
	v_max_f32_e32 v115, v108, v108
	v_max_f32_e32 v112, v112, v112
	v_max_f32_e32 v120, v109, v109
	v_max_f32_e32 v113, v113, v113
	v_max_f32_e32 v106, 0x1e3ce508, v106
	v_max_f32_e32 v108, 0x1e3ce508, v110
	v_max_f32_e32 v107, 0x1e3ce508, v107
	v_max_f32_e32 v109, 0x1e3ce508, v111
	v_max_f32_e32 v110, 0x1e3ce508, v115
	v_max_f32_e32 v112, 0x1e3ce508, v112
	v_max_f32_e32 v111, 0x1e3ce508, v120
	v_max_f32_e32 v113, 0x1e3ce508, v113
	v_pk_mul_f32 v[104:105], v[104:105], v[110:111]
	v_pk_mul_f32 v[102:103], v[102:103], v[106:107]
	v_pk_mul_f32 v[106:107], v[100:101], v[112:113]
	v_pk_mul_f32 v[100:101], v[98:99], v[108:109]
	v_cvt_pk_bf16_f32 v98, v102, v103
	v_cvt_pk_bf16_f32 v99, v104, v105
	v_ashrrev_i32_e32 v115, 31, v114
	v_cvt_pk_bf16_f32 v100, v100, v101
	v_cvt_pk_bf16_f32 v101, v106, v107
	global_load_dwordx4 v[102:105], v[116:117], off nt
	s_nop 0
	global_store_dwordx4 v[118:119], v[98:101], off offset:256
	s_waitcnt vmcnt(1)
	s_nop 0
	v_lshlrev_b32_e32 v98, 16, v102
	v_and_b32_e32 v99, 0xffff0000, v102
	v_lshlrev_b32_e32 v100, 16, v103
	v_and_b32_e32 v101, 0xffff0000, v103
	v_lshlrev_b32_e32 v102, 16, v104
	v_and_b32_e32 v103, 0xffff0000, v104
	v_lshlrev_b32_e32 v104, 16, v105
	v_and_b32_e32 v105, 0xffff0000, v105
	v_max_f32_e32 v98, v98, v98
	v_max_f32_e32 v102, v102, v102
	v_max_f32_e32 v99, v99, v99
	v_max_f32_e32 v103, v103, v103
	v_max_f32_e32 v106, v100, v100
	v_max_f32_e32 v104, v104, v104
	v_max_f32_e32 v107, v101, v101
	v_max_f32_e32 v105, v105, v105
	v_max_f32_e32 v98, 0x1e3ce508, v98
	v_max_f32_e32 v100, 0x1e3ce508, v102
	v_max_f32_e32 v99, 0x1e3ce508, v99
	v_max_f32_e32 v101, 0x1e3ce508, v103
	v_max_f32_e32 v102, 0x1e3ce508, v106
	v_max_f32_e32 v104, 0x1e3ce508, v104
	v_max_f32_e32 v103, 0x1e3ce508, v107
	v_max_f32_e32 v105, 0x1e3ce508, v105
	v_pk_mul_f32 v[96:97], v[96:97], v[102:103]
	v_pk_mul_f32 v[94:95], v[94:95], v[98:99]
	v_pk_mul_f32 v[98:99], v[92:93], v[104:105]
	v_pk_mul_f32 v[92:93], v[90:91], v[100:101]
	v_cvt_pk_bf16_f32 v90, v94, v95
	v_cvt_pk_bf16_f32 v91, v96, v97
	v_lshlrev_b64 v[102:103], 12, v[114:115]
	v_cvt_pk_bf16_f32 v92, v92, v93
	v_cvt_pk_bf16_f32 v93, v98, v99
	global_load_dwordx4 v[94:97], v[116:117], off offset:256 nt
	v_lshl_add_u64 v[102:103], s[4:5], 0, v[102:103]
	v_lshl_add_u64 v[102:103], v[102:103], 0, v[186:187]
	global_store_dwordx4 v[102:103], v[90:93], off
	v_or_b32_e32 v98, 48, v188
	v_mad_i64_i32 v[100:101], s[6:7], v98, s46, v[130:131]
	v_lshl_add_u64 v[100:101], v[100:101], 0, v[186:187]
	s_waitcnt vmcnt(1)
	v_lshlrev_b32_e32 v90, 16, v94
	v_and_b32_e32 v91, 0xffff0000, v94
	v_lshlrev_b32_e32 v92, 16, v95
	v_and_b32_e32 v93, 0xffff0000, v95
	v_lshlrev_b32_e32 v94, 16, v96
	v_and_b32_e32 v95, 0xffff0000, v96
	v_lshlrev_b32_e32 v96, 16, v97
	v_and_b32_e32 v97, 0xffff0000, v97
	v_max_f32_e32 v90, v90, v90
	v_max_f32_e32 v94, v94, v94
	v_max_f32_e32 v91, v91, v91
	v_max_f32_e32 v95, v95, v95
	v_max_f32_e32 v99, v92, v92
	v_max_f32_e32 v96, v96, v96
	v_max_f32_e32 v104, v93, v93
	v_max_f32_e32 v97, v97, v97
	v_max_f32_e32 v90, 0x1e3ce508, v90
	v_max_f32_e32 v92, 0x1e3ce508, v94
	v_max_f32_e32 v91, 0x1e3ce508, v91
	v_max_f32_e32 v93, 0x1e3ce508, v95
	v_max_f32_e32 v94, 0x1e3ce508, v99
	v_max_f32_e32 v96, 0x1e3ce508, v96
	v_max_f32_e32 v95, 0x1e3ce508, v104
	v_max_f32_e32 v97, 0x1e3ce508, v97
	v_pk_mul_f32 v[88:89], v[88:89], v[94:95]
	v_pk_mul_f32 v[86:87], v[86:87], v[90:91]
	v_pk_mul_f32 v[90:91], v[84:85], v[96:97]
	v_pk_mul_f32 v[84:85], v[82:83], v[92:93]
	v_cvt_pk_bf16_f32 v82, v86, v87
	v_cvt_pk_bf16_f32 v83, v88, v89
	v_ashrrev_i32_e32 v99, 31, v98
	v_cvt_pk_bf16_f32 v84, v84, v85
	v_cvt_pk_bf16_f32 v85, v90, v91
	global_load_dwordx4 v[86:89], v[100:101], off nt
	s_nop 0
	global_store_dwordx4 v[102:103], v[82:85], off offset:256
	s_waitcnt vmcnt(1)
	s_nop 0
	v_lshlrev_b32_e32 v82, 16, v86
	v_and_b32_e32 v83, 0xffff0000, v86
	v_lshlrev_b32_e32 v84, 16, v87
	v_and_b32_e32 v85, 0xffff0000, v87
	v_lshlrev_b32_e32 v86, 16, v88
	v_and_b32_e32 v87, 0xffff0000, v88
	v_lshlrev_b32_e32 v88, 16, v89
	v_and_b32_e32 v89, 0xffff0000, v89
	v_max_f32_e32 v82, v82, v82
	v_max_f32_e32 v86, v86, v86
	v_max_f32_e32 v83, v83, v83
	v_max_f32_e32 v87, v87, v87
	v_max_f32_e32 v90, v84, v84
	v_max_f32_e32 v88, v88, v88
	v_max_f32_e32 v91, v85, v85
	v_max_f32_e32 v89, v89, v89
	v_max_f32_e32 v82, 0x1e3ce508, v82
	v_max_f32_e32 v84, 0x1e3ce508, v86
	v_max_f32_e32 v83, 0x1e3ce508, v83
	v_max_f32_e32 v85, 0x1e3ce508, v87
	v_max_f32_e32 v86, 0x1e3ce508, v90
	v_max_f32_e32 v88, 0x1e3ce508, v88
	v_max_f32_e32 v87, 0x1e3ce508, v91
	v_max_f32_e32 v89, 0x1e3ce508, v89
	v_pk_mul_f32 v[80:81], v[80:81], v[86:87]
	v_pk_mul_f32 v[78:79], v[78:79], v[82:83]
	v_pk_mul_f32 v[82:83], v[76:77], v[88:89]
	v_pk_mul_f32 v[76:77], v[74:75], v[84:85]
	v_cvt_pk_bf16_f32 v74, v78, v79
	v_cvt_pk_bf16_f32 v75, v80, v81
	v_lshlrev_b64 v[86:87], 12, v[98:99]
	v_cvt_pk_bf16_f32 v76, v76, v77
	v_cvt_pk_bf16_f32 v77, v82, v83
	global_load_dwordx4 v[78:81], v[100:101], off offset:256 nt
	v_lshl_add_u64 v[86:87], s[4:5], 0, v[86:87]
	v_lshl_add_u64 v[86:87], v[86:87], 0, v[186:187]
	global_store_dwordx4 v[86:87], v[74:77], off
	v_add_u32_e32 v82, 0x80, v188
	v_mad_i64_i32 v[84:85], s[6:7], v82, s46, v[130:131]
	v_lshl_add_u64 v[84:85], v[84:85], 0, v[186:187]
	s_waitcnt vmcnt(1)
	v_lshlrev_b32_e32 v74, 16, v78
	v_and_b32_e32 v75, 0xffff0000, v78
	v_lshlrev_b32_e32 v76, 16, v79
	v_and_b32_e32 v77, 0xffff0000, v79
	v_lshlrev_b32_e32 v78, 16, v80
	v_and_b32_e32 v79, 0xffff0000, v80
	v_lshlrev_b32_e32 v80, 16, v81
	v_and_b32_e32 v81, 0xffff0000, v81
	v_max_f32_e32 v74, v74, v74
	v_max_f32_e32 v78, v78, v78
	v_max_f32_e32 v75, v75, v75
	v_max_f32_e32 v79, v79, v79
	v_max_f32_e32 v83, v76, v76
	v_max_f32_e32 v80, v80, v80
	v_max_f32_e32 v88, v77, v77
	v_max_f32_e32 v81, v81, v81
	v_max_f32_e32 v74, 0x1e3ce508, v74
	v_max_f32_e32 v76, 0x1e3ce508, v78
	v_max_f32_e32 v75, 0x1e3ce508, v75
	v_max_f32_e32 v77, 0x1e3ce508, v79
	v_max_f32_e32 v78, 0x1e3ce508, v83
	v_max_f32_e32 v80, 0x1e3ce508, v80
	v_max_f32_e32 v79, 0x1e3ce508, v88
	v_max_f32_e32 v81, 0x1e3ce508, v81
	v_pk_mul_f32 v[72:73], v[72:73], v[78:79]
	v_pk_mul_f32 v[70:71], v[70:71], v[74:75]
	v_pk_mul_f32 v[74:75], v[68:69], v[80:81]
	v_pk_mul_f32 v[68:69], v[66:67], v[76:77]
	v_cvt_pk_bf16_f32 v66, v70, v71
	v_cvt_pk_bf16_f32 v67, v72, v73
	v_ashrrev_i32_e32 v83, 31, v82
	v_cvt_pk_bf16_f32 v68, v68, v69
	v_cvt_pk_bf16_f32 v69, v74, v75
	global_load_dwordx4 v[70:73], v[84:85], off nt
	s_nop 0
	global_store_dwordx4 v[86:87], v[66:69], off offset:256
	s_waitcnt vmcnt(1)
	s_nop 0
	v_lshlrev_b32_e32 v66, 16, v70
	v_and_b32_e32 v67, 0xffff0000, v70
	v_lshlrev_b32_e32 v68, 16, v71
	v_and_b32_e32 v69, 0xffff0000, v71
	v_lshlrev_b32_e32 v70, 16, v72
	v_and_b32_e32 v71, 0xffff0000, v72
	v_lshlrev_b32_e32 v72, 16, v73
	v_and_b32_e32 v73, 0xffff0000, v73
	v_max_f32_e32 v66, v66, v66
	v_max_f32_e32 v70, v70, v70
	v_max_f32_e32 v67, v67, v67
	v_max_f32_e32 v71, v71, v71
	v_max_f32_e32 v74, v68, v68
	v_max_f32_e32 v72, v72, v72
	v_max_f32_e32 v75, v69, v69
	v_max_f32_e32 v73, v73, v73
	v_max_f32_e32 v66, 0x1e3ce508, v66
	v_max_f32_e32 v68, 0x1e3ce508, v70
	v_max_f32_e32 v67, 0x1e3ce508, v67
	v_max_f32_e32 v69, 0x1e3ce508, v71
	v_max_f32_e32 v70, 0x1e3ce508, v74
	v_max_f32_e32 v72, 0x1e3ce508, v72
	v_max_f32_e32 v71, 0x1e3ce508, v75
	v_max_f32_e32 v73, 0x1e3ce508, v73
	v_pk_mul_f32 v[64:65], v[64:65], v[70:71]
	v_pk_mul_f32 v[62:63], v[62:63], v[66:67]
	v_pk_mul_f32 v[66:67], v[60:61], v[72:73]
	v_pk_mul_f32 v[60:61], v[58:59], v[68:69]
	v_cvt_pk_bf16_f32 v58, v62, v63
	v_cvt_pk_bf16_f32 v59, v64, v65
	v_lshlrev_b64 v[70:71], 12, v[82:83]
	v_cvt_pk_bf16_f32 v60, v60, v61
	v_cvt_pk_bf16_f32 v61, v66, v67
	global_load_dwordx4 v[62:65], v[84:85], off offset:256 nt
	v_lshl_add_u64 v[70:71], s[4:5], 0, v[70:71]
	v_lshl_add_u64 v[70:71], v[70:71], 0, v[186:187]
	global_store_dwordx4 v[70:71], v[58:61], off
	v_add_u32_e32 v66, 0x90, v188
	v_mad_i64_i32 v[68:69], s[6:7], v66, s46, v[130:131]
	v_lshl_add_u64 v[68:69], v[68:69], 0, v[186:187]
	s_waitcnt vmcnt(1)
	v_lshlrev_b32_e32 v58, 16, v62
	v_and_b32_e32 v59, 0xffff0000, v62
	v_lshlrev_b32_e32 v60, 16, v63
	v_and_b32_e32 v61, 0xffff0000, v63
	v_lshlrev_b32_e32 v62, 16, v64
	v_and_b32_e32 v63, 0xffff0000, v64
	v_lshlrev_b32_e32 v64, 16, v65
	v_and_b32_e32 v65, 0xffff0000, v65
	v_max_f32_e32 v58, v58, v58
	v_max_f32_e32 v62, v62, v62
	v_max_f32_e32 v59, v59, v59
	v_max_f32_e32 v63, v63, v63
	v_max_f32_e32 v67, v60, v60
	v_max_f32_e32 v64, v64, v64
	v_max_f32_e32 v72, v61, v61
	v_max_f32_e32 v65, v65, v65
	v_max_f32_e32 v58, 0x1e3ce508, v58
	v_max_f32_e32 v60, 0x1e3ce508, v62
	v_max_f32_e32 v59, 0x1e3ce508, v59
	v_max_f32_e32 v61, 0x1e3ce508, v63
	v_max_f32_e32 v62, 0x1e3ce508, v67
	v_max_f32_e32 v64, 0x1e3ce508, v64
	v_max_f32_e32 v63, 0x1e3ce508, v72
	v_max_f32_e32 v65, 0x1e3ce508, v65
	v_pk_mul_f32 v[56:57], v[56:57], v[62:63]
	v_pk_mul_f32 v[54:55], v[54:55], v[58:59]
	v_pk_mul_f32 v[58:59], v[52:53], v[64:65]
	v_pk_mul_f32 v[52:53], v[50:51], v[60:61]
	v_cvt_pk_bf16_f32 v50, v54, v55
	v_cvt_pk_bf16_f32 v51, v56, v57
	v_ashrrev_i32_e32 v67, 31, v66
	v_cvt_pk_bf16_f32 v52, v52, v53
	v_cvt_pk_bf16_f32 v53, v58, v59
	global_load_dwordx4 v[54:57], v[68:69], off nt
	s_nop 0
	global_store_dwordx4 v[70:71], v[50:53], off offset:256
	s_waitcnt vmcnt(1)
	s_nop 0
	v_lshlrev_b32_e32 v50, 16, v54
	v_and_b32_e32 v51, 0xffff0000, v54
	v_lshlrev_b32_e32 v52, 16, v55
	v_and_b32_e32 v53, 0xffff0000, v55
	v_lshlrev_b32_e32 v54, 16, v56
	v_and_b32_e32 v55, 0xffff0000, v56
	v_lshlrev_b32_e32 v56, 16, v57
	v_and_b32_e32 v57, 0xffff0000, v57
	v_max_f32_e32 v50, v50, v50
	v_max_f32_e32 v54, v54, v54
	v_max_f32_e32 v51, v51, v51
	v_max_f32_e32 v55, v55, v55
	v_max_f32_e32 v58, v52, v52
	v_max_f32_e32 v56, v56, v56
	v_max_f32_e32 v59, v53, v53
	v_max_f32_e32 v57, v57, v57
	v_max_f32_e32 v50, 0x1e3ce508, v50
	v_max_f32_e32 v52, 0x1e3ce508, v54
	v_max_f32_e32 v51, 0x1e3ce508, v51
	v_max_f32_e32 v53, 0x1e3ce508, v55
	v_max_f32_e32 v54, 0x1e3ce508, v58
	v_max_f32_e32 v56, 0x1e3ce508, v56
	v_max_f32_e32 v55, 0x1e3ce508, v59
	v_max_f32_e32 v57, 0x1e3ce508, v57
	v_pk_mul_f32 v[48:49], v[48:49], v[54:55]
	v_pk_mul_f32 v[46:47], v[46:47], v[50:51]
	v_pk_mul_f32 v[50:51], v[44:45], v[56:57]
	v_pk_mul_f32 v[44:45], v[42:43], v[52:53]
	v_cvt_pk_bf16_f32 v42, v46, v47
	v_cvt_pk_bf16_f32 v43, v48, v49
	v_lshlrev_b64 v[54:55], 12, v[66:67]
	v_cvt_pk_bf16_f32 v44, v44, v45
	v_cvt_pk_bf16_f32 v45, v50, v51
	global_load_dwordx4 v[46:49], v[68:69], off offset:256 nt
	v_lshl_add_u64 v[54:55], s[4:5], 0, v[54:55]
	v_lshl_add_u64 v[54:55], v[54:55], 0, v[186:187]
	global_store_dwordx4 v[54:55], v[42:45], off
	v_add_u32_e32 v50, 0xa0, v188
	v_mad_i64_i32 v[52:53], s[6:7], v50, s46, v[130:131]
	v_lshl_add_u64 v[52:53], v[52:53], 0, v[186:187]
	s_waitcnt vmcnt(1)
	v_lshlrev_b32_e32 v42, 16, v46
	v_and_b32_e32 v43, 0xffff0000, v46
	v_lshlrev_b32_e32 v44, 16, v47
	v_and_b32_e32 v45, 0xffff0000, v47
	v_lshlrev_b32_e32 v46, 16, v48
	v_and_b32_e32 v47, 0xffff0000, v48
	v_lshlrev_b32_e32 v48, 16, v49
	v_and_b32_e32 v49, 0xffff0000, v49
	v_max_f32_e32 v42, v42, v42
	v_max_f32_e32 v46, v46, v46
	v_max_f32_e32 v43, v43, v43
	v_max_f32_e32 v47, v47, v47
	v_max_f32_e32 v51, v44, v44
	v_max_f32_e32 v48, v48, v48
	v_max_f32_e32 v56, v45, v45
	v_max_f32_e32 v49, v49, v49
	v_max_f32_e32 v42, 0x1e3ce508, v42
	v_max_f32_e32 v44, 0x1e3ce508, v46
	v_max_f32_e32 v43, 0x1e3ce508, v43
	v_max_f32_e32 v45, 0x1e3ce508, v47
	v_max_f32_e32 v46, 0x1e3ce508, v51
	v_max_f32_e32 v48, 0x1e3ce508, v48
	v_max_f32_e32 v47, 0x1e3ce508, v56
	v_max_f32_e32 v49, 0x1e3ce508, v49
	v_pk_mul_f32 v[40:41], v[40:41], v[46:47]
	v_pk_mul_f32 v[38:39], v[38:39], v[42:43]
	v_pk_mul_f32 v[42:43], v[36:37], v[48:49]
	v_pk_mul_f32 v[36:37], v[34:35], v[44:45]
	v_cvt_pk_bf16_f32 v34, v38, v39
	v_cvt_pk_bf16_f32 v35, v40, v41
	v_ashrrev_i32_e32 v51, 31, v50
	v_cvt_pk_bf16_f32 v36, v36, v37
	v_cvt_pk_bf16_f32 v37, v42, v43
	global_load_dwordx4 v[38:41], v[52:53], off nt
	s_nop 0
	global_store_dwordx4 v[54:55], v[34:37], off offset:256
	s_waitcnt vmcnt(1)
	s_nop 0
	v_lshlrev_b32_e32 v34, 16, v38
	v_and_b32_e32 v35, 0xffff0000, v38
	v_lshlrev_b32_e32 v36, 16, v39
	v_and_b32_e32 v37, 0xffff0000, v39
	v_lshlrev_b32_e32 v38, 16, v40
	v_and_b32_e32 v39, 0xffff0000, v40
	v_lshlrev_b32_e32 v40, 16, v41
	v_and_b32_e32 v41, 0xffff0000, v41
	v_max_f32_e32 v34, v34, v34
	v_max_f32_e32 v38, v38, v38
	v_max_f32_e32 v35, v35, v35
	v_max_f32_e32 v39, v39, v39
	v_max_f32_e32 v42, v36, v36
	v_max_f32_e32 v40, v40, v40
	v_max_f32_e32 v43, v37, v37
	v_max_f32_e32 v41, v41, v41
	v_max_f32_e32 v34, 0x1e3ce508, v34
	v_max_f32_e32 v36, 0x1e3ce508, v38
	v_max_f32_e32 v35, 0x1e3ce508, v35
	v_max_f32_e32 v37, 0x1e3ce508, v39
	v_max_f32_e32 v38, 0x1e3ce508, v42
	v_max_f32_e32 v40, 0x1e3ce508, v40
	v_max_f32_e32 v39, 0x1e3ce508, v43
	v_max_f32_e32 v41, 0x1e3ce508, v41
	v_pk_mul_f32 v[32:33], v[32:33], v[38:39]
	v_pk_mul_f32 v[30:31], v[30:31], v[34:35]
	v_pk_mul_f32 v[34:35], v[28:29], v[40:41]
	v_pk_mul_f32 v[28:29], v[26:27], v[36:37]
	v_cvt_pk_bf16_f32 v26, v30, v31
	v_cvt_pk_bf16_f32 v27, v32, v33
	v_lshlrev_b64 v[38:39], 12, v[50:51]
	v_cvt_pk_bf16_f32 v28, v28, v29
	v_cvt_pk_bf16_f32 v29, v34, v35
	global_load_dwordx4 v[30:33], v[52:53], off offset:256 nt
	v_lshl_add_u64 v[38:39], s[4:5], 0, v[38:39]
	v_lshl_add_u64 v[38:39], v[38:39], 0, v[186:187]
	global_store_dwordx4 v[38:39], v[26:29], off
	v_add_u32_e32 v34, 0xb0, v188
	v_mad_i64_i32 v[36:37], s[6:7], v34, s46, v[130:131]
	v_lshl_add_u64 v[36:37], v[36:37], 0, v[186:187]
	s_waitcnt vmcnt(1)
	v_lshlrev_b32_e32 v26, 16, v30
	v_and_b32_e32 v27, 0xffff0000, v30
	v_lshlrev_b32_e32 v28, 16, v31
	v_and_b32_e32 v29, 0xffff0000, v31
	v_lshlrev_b32_e32 v30, 16, v32
	v_and_b32_e32 v31, 0xffff0000, v32
	v_lshlrev_b32_e32 v32, 16, v33
	v_and_b32_e32 v33, 0xffff0000, v33
	v_max_f32_e32 v26, v26, v26
	v_max_f32_e32 v30, v30, v30
	v_max_f32_e32 v27, v27, v27
	v_max_f32_e32 v31, v31, v31
	v_max_f32_e32 v35, v28, v28
	v_max_f32_e32 v32, v32, v32
	v_max_f32_e32 v40, v29, v29
	v_max_f32_e32 v33, v33, v33
	v_max_f32_e32 v26, 0x1e3ce508, v26
	v_max_f32_e32 v28, 0x1e3ce508, v30
	v_max_f32_e32 v27, 0x1e3ce508, v27
	v_max_f32_e32 v29, 0x1e3ce508, v31
	v_max_f32_e32 v30, 0x1e3ce508, v35
	v_max_f32_e32 v32, 0x1e3ce508, v32
	v_max_f32_e32 v31, 0x1e3ce508, v40
	v_max_f32_e32 v33, 0x1e3ce508, v33
	v_pk_mul_f32 v[24:25], v[24:25], v[30:31]
	v_pk_mul_f32 v[22:23], v[22:23], v[26:27]
	v_pk_mul_f32 v[26:27], v[20:21], v[32:33]
	v_pk_mul_f32 v[20:21], v[18:19], v[28:29]
	v_cvt_pk_bf16_f32 v18, v22, v23
	v_cvt_pk_bf16_f32 v19, v24, v25
	v_ashrrev_i32_e32 v35, 31, v34
	v_cvt_pk_bf16_f32 v20, v20, v21
	v_cvt_pk_bf16_f32 v21, v26, v27
	global_load_dwordx4 v[22:25], v[36:37], off nt
	s_nop 0
	global_store_dwordx4 v[38:39], v[18:21], off offset:256
	s_waitcnt vmcnt(1)
	s_nop 0
	v_lshlrev_b32_e32 v18, 16, v22
	v_and_b32_e32 v19, 0xffff0000, v22
	v_lshlrev_b32_e32 v20, 16, v23
	v_and_b32_e32 v21, 0xffff0000, v23
	v_lshlrev_b32_e32 v22, 16, v24
	v_and_b32_e32 v23, 0xffff0000, v24
	v_lshlrev_b32_e32 v24, 16, v25
	v_and_b32_e32 v25, 0xffff0000, v25
	v_max_f32_e32 v18, v18, v18
	v_max_f32_e32 v22, v22, v22
	v_max_f32_e32 v19, v19, v19
	v_max_f32_e32 v23, v23, v23
	v_max_f32_e32 v26, v20, v20
	v_max_f32_e32 v24, v24, v24
	v_max_f32_e32 v27, v21, v21
	v_max_f32_e32 v25, v25, v25
	v_max_f32_e32 v18, 0x1e3ce508, v18
	v_max_f32_e32 v20, 0x1e3ce508, v22
	v_max_f32_e32 v19, 0x1e3ce508, v19
	v_max_f32_e32 v21, 0x1e3ce508, v23
	v_max_f32_e32 v22, 0x1e3ce508, v26
	v_max_f32_e32 v24, 0x1e3ce508, v24
	v_max_f32_e32 v23, 0x1e3ce508, v27
	v_max_f32_e32 v25, 0x1e3ce508, v25
	v_pk_mul_f32 v[16:17], v[16:17], v[22:23]
	v_pk_mul_f32 v[14:15], v[14:15], v[18:19]
	v_pk_mul_f32 v[18:19], v[12:13], v[24:25]
	v_pk_mul_f32 v[12:13], v[10:11], v[20:21]
	v_cvt_pk_bf16_f32 v10, v14, v15
	v_cvt_pk_bf16_f32 v11, v16, v17
	s_nop 0
	v_cvt_pk_bf16_f32 v12, v12, v13
	v_cvt_pk_bf16_f32 v13, v18, v19
	global_load_dwordx4 v[14:17], v[36:37], off offset:256 nt
	v_lshlrev_b64 v[18:19], 12, v[34:35]
	v_lshl_add_u64 v[18:19], s[4:5], 0, v[18:19]
	v_lshl_add_u64 v[18:19], v[18:19], 0, v[186:187]
	global_store_dwordx4 v[18:19], v[10:13], off
	s_waitcnt vmcnt(1)
	s_nop 0
	v_lshlrev_b32_e32 v10, 16, v14
	v_and_b32_e32 v11, 0xffff0000, v14
	v_lshlrev_b32_e32 v12, 16, v15
	v_and_b32_e32 v13, 0xffff0000, v15
	v_lshlrev_b32_e32 v14, 16, v16
	v_and_b32_e32 v15, 0xffff0000, v16
	v_lshlrev_b32_e32 v16, 16, v17
	v_and_b32_e32 v17, 0xffff0000, v17
	v_max_f32_e32 v10, v10, v10
	v_max_f32_e32 v14, v14, v14
	v_max_f32_e32 v11, v11, v11
	v_max_f32_e32 v15, v15, v15
	v_max_f32_e32 v16, v16, v16
	v_max_f32_e32 v17, v17, v17
	v_max_f32_e32 v20, v12, v12
	v_max_f32_e32 v21, v13, v13
	v_max_f32_e32 v10, 0x1e3ce508, v10
	v_max_f32_e32 v12, 0x1e3ce508, v14
	v_max_f32_e32 v11, 0x1e3ce508, v11
	v_max_f32_e32 v13, 0x1e3ce508, v15
	v_max_f32_e32 v16, 0x1e3ce508, v16
	v_max_f32_e32 v17, 0x1e3ce508, v17
	v_max_f32_e32 v14, 0x1e3ce508, v20
	v_max_f32_e32 v15, 0x1e3ce508, v21
	v_pk_mul_f32 v[6:7], v[6:7], v[10:11]
	v_pk_mul_f32 v[10:11], v[4:5], v[16:17]
	v_pk_mul_f32 v[4:5], v[2:3], v[12:13]
	v_pk_mul_f32 v[8:9], v[8:9], v[14:15]
	v_cvt_pk_bf16_f32 v2, v6, v7
	s_nop 0
	v_cvt_pk_bf16_f32 v3, v8, v9
	v_cvt_pk_bf16_f32 v4, v4, v5
	v_cvt_pk_bf16_f32 v5, v10, v11
	global_store_dwordx4 v[18:19], v[2:5], off offset:256
	s_cbranch_vccnz .LBB0_893
	s_andn2_b64 vcc, exec, s[8:9]
	s_cbranch_vccnz .LBB0_892
	s_barrier
	s_branch .LBB0_892
